# attention: the four 384-cycle stagger sleeps for waves 4-7 behind the stage barrier removed again (waves start each key tile together); on v085
# baseline (speedup 1.0000x reference)
.LBB0_364:
	s_and_saveexec_b64 s[0:1], s[2:3]
	s_nop 2
	v_mov_b32_e32 v32, s59
	v_mov_b32_e32 v33, s17
	ds_write_b32 v32, v33 offset:40960
	s_or_b64 exec, exec, s[0:1]
	s_waitcnt lgkmcnt(0)
	s_barrier
	s_waitcnt vmcnt(3)
	ds_write_b128 v164, v[80:83]
	s_waitcnt vmcnt(2)
	ds_write_b128 v164, v[84:87] offset:18432
	s_waitcnt vmcnt(1)
	ds_write_b128 v166, v[88:91]
	s_waitcnt vmcnt(0)
	ds_write_b128 v166, v[92:95] offset:18432
	ds_read_b128 v[32:35], v129 offset:40960
	ds_read_b128 v[36:39], v129 offset:40976
	s_mov_b64 s[0:1], -1
	s_waitcnt lgkmcnt(0)
	s_barrier
	s_cselect_b32 s100, 1, 0
	s_cmp_lt_u32 s99, 0x100
	s_cbranch_scc1 .Lstg_3
.Lstg_3:
	s_cmp_lg_u32 s100, 0
	v_and_b32_e32 v32, v32, v33
	v_and_b32_e32 v32, v32, v34
	v_and_b32_e32 v32, v32, v35
	v_and_b32_e32 v32, v32, v36
	v_and_b32_e32 v32, v32, v37
	v_and_b32_e32 v32, v32, v38
	v_and_b32_e32 v32, v32, v39
	v_and_b32_e32 v32, 1, v32
	v_cmp_eq_u32_e32 vcc, 1, v32
	s_cbranch_vccz .LBB0_368
	s_and_b64 vcc, exec, s[0:1]
	s_cbranch_vccz .LBB0_364
	s_branch .LBB0_443

.LBB0_392:
	s_and_saveexec_b64 s[0:1], s[2:3]
	s_nop 4
	v_mov_b32_e32 v32, s59
	v_mov_b32_e32 v33, s17
	ds_write_b32 v32, v33 offset:40960
	s_or_b64 exec, exec, s[0:1]
	s_waitcnt lgkmcnt(0)
	s_barrier
	s_waitcnt vmcnt(3)
	ds_write_b128 v164, v[100:103]
	s_waitcnt vmcnt(2)
	ds_write_b128 v164, v[96:99] offset:18432
	s_waitcnt vmcnt(1)
	ds_write_b128 v166, v[108:111]
	s_waitcnt vmcnt(0)
	ds_write_b128 v166, v[104:107] offset:18432
	ds_read_b128 v[32:35], v129 offset:40960
	ds_read_b128 v[36:39], v129 offset:40976
	s_mov_b64 s[0:1], -1
	s_waitcnt lgkmcnt(0)
	s_barrier
	s_cselect_b32 s100, 1, 0
	s_cmp_lt_u32 s99, 0x100
	s_cbranch_scc1 .Lstg_2
.Lstg_2:
	s_cmp_lg_u32 s100, 0
	v_and_b32_e32 v32, v32, v33
	v_and_b32_e32 v32, v32, v34
	v_and_b32_e32 v32, v32, v35
	v_and_b32_e32 v32, v32, v36
	v_and_b32_e32 v32, v32, v37
	v_and_b32_e32 v32, v32, v38
	v_and_b32_e32 v32, v32, v39
	v_and_b32_e32 v32, 1, v32
	v_cmp_eq_u32_e32 vcc, 1, v32
	s_cbranch_vccz .LBB0_408
	s_and_b64 vcc, exec, s[0:1]
	s_cbranch_vccz .LBB0_364
	s_branch .LBB0_443

.LBB0_447:
	s_lshl_b32 s59, s57, 7
	s_cmp_lt_u32 s57, 2
	s_waitcnt vmcnt(3)
	ds_write_b128 v200, v[80:83]
	s_waitcnt vmcnt(2)
	ds_write_b128 v200, v[84:87] offset:18432
	s_waitcnt vmcnt(1)
	ds_write_b128 v201, v[88:91]
	s_waitcnt vmcnt(0)
	ds_write_b128 v201, v[92:95] offset:18432
	s_waitcnt lgkmcnt(0)
	s_barrier
	s_cselect_b32 s100, 1, 0
	s_cmp_lt_u32 s99, 0x100
	s_cbranch_scc1 .Lstg_1
.Lstg_1:
	s_cmp_lg_u32 s100, 0
	s_cbranch_scc1 .LBB0_449
	s_add_i32 s0, s59, 0xffffff00
	v_add_u32_e32 v32, s0, v198
	v_ashrrev_i32_e32 v33, 31, v32
	v_lshlrev_b64 v[32:33], 7, v[32:33]
	v_lshl_add_u64 v[34:35], v[166:167], 0, v[32:33]
	v_lshl_add_u64 v[32:33], v[168:169], 0, v[32:33]
	global_load_dwordx4 v[80:83], v[34:35], off
	global_load_dwordx4 v[84:87], v[32:33], off
	v_add_u32_e32 v32, s0, v199
	v_ashrrev_i32_e32 v33, 31, v32
	v_lshlrev_b64 v[32:33], 7, v[32:33]
	v_lshl_add_u64 v[34:35], v[170:171], 0, v[32:33]
	v_lshl_add_u64 v[32:33], v[172:173], 0, v[32:33]
	global_load_dwordx4 v[88:91], v[34:35], off
	global_load_dwordx4 v[92:95], v[32:33], off

.LBB0_484:
	s_cmp_lt_u32 s57, 3
	s_waitcnt vmcnt(3)
	ds_write_b128 v200, v[96:99] offset:45056
	s_waitcnt vmcnt(2)
	ds_write_b128 v200, v[100:103] offset:63488
	s_waitcnt vmcnt(1)
	ds_write_b128 v201, v[104:107] offset:45056
	s_waitcnt vmcnt(0)
	ds_write_b128 v201, v[108:111] offset:63488
	s_waitcnt lgkmcnt(0)
	s_barrier
	s_cselect_b32 s100, 1, 0
	s_cmp_lt_u32 s99, 0x100
	s_cbranch_scc1 .Lstg_0
.Lstg_0:
	s_cmp_lg_u32 s100, 0
	s_cbranch_scc1 .LBB0_486
	s_add_i32 s0, s59, 0xfffffe80
	v_add_u32_e32 v32, s0, v198
	v_ashrrev_i32_e32 v33, 31, v32
	v_lshlrev_b64 v[32:33], 7, v[32:33]
	v_lshl_add_u64 v[34:35], v[166:167], 0, v[32:33]
	v_lshl_add_u64 v[32:33], v[168:169], 0, v[32:33]
	global_load_dwordx4 v[96:99], v[34:35], off
	global_load_dwordx4 v[100:103], v[32:33], off
	v_add_u32_e32 v32, s0, v199
	v_ashrrev_i32_e32 v33, 31, v32
	v_lshlrev_b64 v[32:33], 7, v[32:33]
	v_lshl_add_u64 v[34:35], v[170:171], 0, v[32:33]
	v_lshl_add_u64 v[32:33], v[172:173], 0, v[32:33]
	global_load_dwordx4 v[104:107], v[34:35], off
	global_load_dwordx4 v[108:111], v[32:33], off
